# kv-up GEMM of phase 3 walks the workgroups in reversed order so the third kv-up round lands on workgroups that had only one q-up tile
# speedup vs baseline: 1.0132x; 1.0077x over previous
; #define LAS __attribute__((address_space(3)))
;     __host__ __device__ bool next(int i, Unit& u) const {
;         if (nsplit > 1 || pm0 > 0) { const long Ls = (long)i * G + c; if (Ls >= (long)nwg * nsplit) return false; const int t = (int)(Ls / nsplit); u.ks = (int)(Ls % nsplit); u.pn = t % nN; u.pm = pm0 + t / nN; return true; }
;         const long L = (long)i * G + c; if (L >= nwg) return false;
;         int wgid = (int)L; { const int q = nwg / NXCD, r = nwg % NXCD, xcd = wgid % NXCD, off = wgid / NXCD; wgid = (xcd < r ? xcd * (q + 1) : r * (q + 1) + (xcd - r) * q) + off; }
;         const int nig = WGM * nN, gid = wgid / nig, fm = gid * WGM, gsz = (nM - fm) < WGM ? (nM - fm) : WGM;
;         u.pm = fm + ((wgid % nig) % gsz); u.pn = (wgid % nig) / gsz; u.ks = 0; return true;
; __global__ void __launch_bounds__(512) mega(Params p) {
;     ...
;                     else if (k == 3 && gi == 0) { g = pg8::Gemm{QL, WL + WO_Q, TT, 768, QRK, QRK};   E.mode = 0; E.a0 = Q; E.ldc = 768; }
;                     else if (k == 3) { g = pg8::Gemm{KVL, WL + WO_KV, TT, 1024, KVRK, KVRK}; E.mode = 4; E.a0 = KV; E.a1 = p.in[15] + L * 128; }
;                     else if (k == 6 && gi == 0) { g = pg8::Gemm{MIX, WL + WO_O, TLAT, DM, DM, DM};    E.mode = 1; E.ldc = 2; E.a0 = xlat; E.a1 = XC; E.a2 = out; E.a3 = XC; E.a4 = modL + 2 * 1024; }
;                     else if (k == 6) { g = pg8::Gemm{MIX, WL + WO_O, TCTX, DM, 128, DM}; nsplit = DM / 128; pm0 = TLAT / 256; E.mode = 3; E.a0 = nullptr; E.a3 = PART_WO; }
;                     else if (k == 8) { g = pg8::Gemm{H, WL + WO_UP, Mact, 2 * DFF, DM, DM}; E.mode = 2; E.a0 = HID; E.a1 = p.in[22] + (size_t)L * 3 * DFF; E.a2 = GE; }
;                     else if (gi == 0) { g = pg8::Gemm{HID, WL + WO_DN, TLAT, DM, DFF, DFF};  E.mode = 1; E.ldc = 1; E.a0 = out; E.a1 = XC; E.a2 = out; E.a3 = XC; E.a4 = modL + 5 * 1024; }
;                     else             { g = pg8::Gemm{HID, WL + WO_DN, TCTX, DM, 256, DFF}; nsplit = DFF / 256; pm0 = TLAT / 256; E.mode = 3; E.a0 = nullptr; E.a3 = PART_DN; }
;                     pg8::StaticOrder S; S.init(g.M, g.N, G, bx); S.nsplit = nsplit; S.pm0 = pm0;
;                     pg8::gemm_phase<pg8::EpiAll, pg8::StaticOrder, true, true>((LAS unsigned char*)lds, g, S, E);
.LBB0_147:
.LBB0_148:
	s_load_dwordx2 s[0:1], s[90:91], 0x78
	v_readlane_b32 s2, v254, 54
	v_readlane_b32 s3, v254, 55
	s_mov_b32 s6, 0
	s_lshl_b64 s[2:3], s[2:3], 2
	v_writelane_b32 v254, s6, 11
	s_waitcnt lgkmcnt(0)
	s_add_u32 s26, s0, s2
	v_readlane_b32 s22, v254, 52
	v_readlane_b32 s78, v254, 34
	v_readlane_b32 s82, v254, 20
	s_mov_b64 s[84:85], 0
	s_mov_b64 s[6:7], 0
	s_addc_u32 s27, s1, s3
	s_mov_b32 s75, 1
	s_mov_b32 s0, 0x8400
	s_mov_b32 s56, 4
	s_movk_i32 s10, 0x80
	v_mov_b32_e32 v251, 0
	s_movk_i32 s16, 0x80
	v_readlane_b32 s23, v254, 53
	v_readlane_b32 s79, v254, 35
	v_readlane_b32 s83, v254, 21
	s_mov_b64 s[50:51], 0
	s_mov_b64 s[24:25], 0
	s_mov_b32 s57, 4
	v_readlane_b32 s1, v253, 6
	s_nop 3
	s_sub_i32 s1, s1, 1
	s_sub_i32 s52, s1, s52
	s_and_b32 s2, s52, 7
	s_lshr_b32 s3, s52, 3
	v_writelane_b32 v253, s2, 8
	v_writelane_b32 v253, s3, 9

; #define LAS __attribute__((address_space(3)))
; __device__ __forceinline__ void prep_tokens(const bf16* Y, bf16* MIX, const float* scw, int tb, int te, int wi, int ws_, int lane) {
;     int inp_ = INP; asm volatile("" : "+s"(inp_));
;     const int ch = 4 * lane, grp = lane >> 4, hw = 1 << grp;
;     const f32x4 cw0 = *(const f32x4*)(scw + ch), cw1 = *(const f32x4*)(scw + 256 + ch), cw2 = *(const f32x4*)(scw + 512 + ch);
;     for (int t0 = tb + wi * 4; t0 < te; t0 += ws_ * 4)
;     for (int ti = 0; ti < 4; ++ti) { const int t = t0 + ti;
;         const bf16* y = Y + (size_t)t * INP; const bool lat = t < TLAT; const int n = lat ? (t & (SEQ - 1)) : ((t - TLAT) & (CTXL - 1)); const int len = lat ? SEQ : CTXL;
;         const bool hp = n > 0, hn = n < len - 1; const long op = hp ? -(long)inp_ : 0, on = hn ? (long)inp_ : 0; const float fp = hp ? 1.f : 0.f, fn = hn ? 1.f : 0.f;
; __global__ void __launch_bounds__(512) mega(Params p) {
;     ...
;                     pg8::StaticOrder S; S.init(g.M, g.N, G, bx); S.nsplit = nsplit; S.pm0 = pm0;
;                     pg8::gemm_phase<pg8::EpiAll, pg8::StaticOrder, true, true>((LAS unsigned char*)lds, g, S, E);
;                 }
;                 if (k == 3) { DEF_TID prep_tokens(Y, MIX, p.in[19] + L * 3 * 256, TLAT, TT, gw, NGW, lane); }
.LBB0_558:
	v_readlane_b32 s52, v253, 47
	s_nop 3
	s_and_b32 s0, s52, 7
	s_lshr_b32 s1, s52, 3
	v_writelane_b32 v253, s0, 8
	v_writelane_b32 v253, s1, 9
	s_nop 0
	v_readlane_b32 s0, v254, 40
	v_readlane_b32 s1, v254, 41
	s_and_b64 vcc, exec, s[0:1]
	s_cbranch_vccz .LBB0_579
	v_mov_b32_e32 v0, v242
	v_readlane_b32 s1, v253, 24
	v_readfirstlane_b32 s0, v0
	s_ashr_i32 s0, s0, 4
	s_and_b32 s0, s0, -4
	s_add_i32 s0, s0, s1
	s_movk_i32 s26, 0x600
	s_cmpk_gt_i32 s0, 0x3ff
	s_cbranch_scc1 .LBB0_579
	v_writelane_b32 v254, s88, 11
	s_load_dwordx2 s[2:3], s[90:91], 0x98
	v_and_b32_e32 v12, 63, v0
	v_writelane_b32 v254, s89, 12
	v_lshlrev_b32_e32 v8, 4, v12
	v_readlane_b32 s1, v254, 5
	s_mul_i32 s4, s1, 0x300
	s_ashr_i32 s5, s4, 31
	s_lshl_b64 s[4:5], s[4:5], 2
	s_waitcnt lgkmcnt(0)
	s_add_u32 s2, s2, s4
	s_addc_u32 s3, s3, s5
	v_bfe_u32 v13, v0, 4, 2
	global_load_dwordx4 v[0:3], v8, s[2:3]
	global_load_dwordx4 v[4:7], v8, s[2:3] offset:2048
	s_add_i32 s28, s0, 0x8000
	global_load_dwordx4 v[8:11], v8, s[2:3] offset:1024
	s_ashr_i32 s27, s26, 31
	s_sub_u32 s2, 0, s26
	s_subb_u32 s3, 0, s27
	s_lshl_b64 s[10:11], s[26:27], 3
	s_sub_u32 s52, 0, s10
	s_subb_u32 s68, 0, s11
	s_lshl_b64 s[12:13], s[26:27], 2
	s_sub_u32 s33, 0, s12
	s_subb_u32 s40, 0, s13
	s_lshl_b64 s[14:15], s[26:27], 1
	s_sub_u32 s1, 0, s14
	s_subb_u32 s69, 0, s15
	s_ashr_i32 s29, s28, 31
	s_mov_b64 s[38:39], s[30:31]
	s_lshl_b64 s[16:17], s[28:29], 11
	s_add_u32 s30, s38, s16
	s_addc_u32 s31, s39, s17
	s_add_u32 s16, s38, 0xa200380
	s_mul_i32 s24, s26, 14
	s_addc_u32 s17, s39, 0
	s_mul_i32 s29, s28, 0xc00
	s_mul_hi_i32 s23, s26, 14
	s_mul_hi_i32 s25, s28, 0xc00
	s_add_u32 s24, s29, s24
	s_addc_u32 s23, s25, s23
	s_add_u32 s34, s16, s24
	s_mul_i32 s22, s26, 12
	s_addc_u32 s35, s17, s23
	s_mul_hi_i32 s21, s26, 12
	s_add_u32 s22, s29, s22
	s_addc_u32 s21, s25, s21
	s_add_u32 s36, s16, s22
	s_addc_u32 s37, s17, s21
	s_add_u32 s46, s38, s29
	s_mul_i32 s20, s26, 10
	s_addc_u32 s47, s39, s25
	s_mul_hi_i32 s19, s26, 10
	s_add_u32 s20, s29, s20
	s_addc_u32 s19, s25, s19
	s_add_u32 s48, s16, s20
	s_addc_u32 s49, s17, s19
	s_add_u32 s10, s29, s10
	s_addc_u32 s11, s25, s11
	s_add_u32 s50, s16, s10
	s_mul_i32 s18, s26, 6
	s_addc_u32 s51, s17, s11
	s_mul_hi_i32 s0, s26, 6
	s_add_u32 s10, s29, s18
	s_addc_u32 s0, s25, s0
	s_add_u32 s54, s16, s10
	s_addc_u32 s55, s17, s0
	s_add_u32 s0, s29, s14
	s_addc_u32 s10, s25, s15
	s_add_u32 s56, s16, s0
	s_addc_u32 s57, s17, s10
	s_add_u32 s0, s29, s12
	s_addc_u32 s10, s25, s13
	s_add_u32 s58, s16, s0
	v_lshlrev_b32_e64 v45, v13, 1
	v_cmp_eq_u32_e64 s[4:5], 3, v13
	v_cmp_lt_u32_e64 s[6:7], 31, v12
	v_cmp_lt_u32_e64 s[8:9], 15, v12
	v_lshlrev_b32_e32 v208, 3, v12
	s_addc_u32 s59, s17, s10
	s_branch .LBB0_562
